# defer 3040 conversion items into idle last-round CUs (7 per WG per window), two ranges per window
# speedup vs baseline: 1.0344x; 1.0115x over previous
; __device__ __forceinline__ unsigned cvt_pk_bf16(float lo, float hi) { unsigned r; asm volatile("v_cvt_pk_bf16_f32 %0, %1, %2" : "=v"(r) : "v"(lo), "v"(hi)); return r; }
; #define LAS __attribute__((address_space(3)))
; __device__ __forceinline__ void tr_item_cu(const float* __restrict__ W, int K, int N, bf16* __restrict__ WT, const float* rowgain, int mode, LAS unsigned char* buf, int item, int wave, int lane) {
;     const int nblk = N >> 7, kb = item / nblk, nb = item - kb * nblk, k0 = 256 * kb, n0 = 128 * nb;
;     const int hr = lane >> 5, c = lane & 31, kw = 32 * wave + 16 * hr;
;     f32x4 v[16];
;     const float* src = W + (size_t)(k0 + kw) * N + n0 + 4 * c;
; #pragma unroll
;     for (int j = 0; j < 16; ++j) v[j] = __builtin_nontemporal_load((const f32x4*)(src + (size_t)j * N));
;     if (rowgain) {
; #pragma unroll
;         for (int q = 0; q < 4; ++q) { const f32x4 r4 = *(const f32x4*)(rowgain + k0 + kw + 4 * q);
; #pragma unroll
;             for (int e = 0; e < 4; ++e) v[4 * q + e] = v[4 * q + e] * r4[e]; }
;     }
; #pragma unroll
;     for (int i = 0; i < 4; ++i) {
;         u32x4 lo, hi;
;         lo.x = pg8::cvt_pk_bf16(v[0][i], v[1][i]);   lo.y = pg8::cvt_pk_bf16(v[2][i], v[3][i]);   lo.z = pg8::cvt_pk_bf16(v[4][i], v[5][i]);   lo.w = pg8::cvt_pk_bf16(v[6][i], v[7][i]);
;         hi.x = pg8::cvt_pk_bf16(v[8][i], v[9][i]);   hi.y = pg8::cvt_pk_bf16(v[10][i], v[11][i]); hi.z = pg8::cvt_pk_bf16(v[12][i], v[13][i]); hi.w = pg8::cvt_pk_bf16(v[14][i], v[15][i]);
;         LAS unsigned char* p = buf + (4 * c + i) * TCP + kw * 2;
;         *(LAS u32x4*)p = lo; *(LAS u32x4*)(p + 16) = hi;
;     }
;     __syncthreads();
; #pragma unroll
;     for (int m = 0; m < 8; ++m) { const int row = 16 * wave + 2 * m + hr;
;         const u32x4 o = *(const LAS u32x4*)(buf + row * TCP + c * 16);
;         asm volatile("global_store_dwordx4 %0, %1, off sc1\n\ts_nop 1" :: "v"(WT + (size_t)row_map(mode, n0 + row) * K + k0 + 8 * c), "v"(o) : "memory"); }
; __global__ void __launch_bounds__(NTHREADS, 2) mega_fwd(Args args) {
;     ...
;         int nbuf = 0;
;         for (int it = bid; it < DEPTH * I_LAYER; it += G, nbuf ^= 1) {
;             const int itr = DEPTH * I_LAYER - 1 - it;
;             const int l = itr / I_LAYER; int r = itr - l * I_LAYER;
.Ldc_pre:
	v_ashrrev_i32_e32 v3, 5, v2
	v_lshl_add_u32 v77, s73, 4, v3
	v_add_u32_e32 v82, 2, v77
	v_lshrrev_b32_e32 v6, 2, v82
	v_and_b32_e32 v84, 16, v6
	v_lshlrev_b32_e32 v6, 2, v82
	v_and_b32_e32 v6, 16, v6
	v_lshrrev_b32_e32 v7, 1, v82
	v_add_u32_e32 v86, 4, v77
	v_and_or_b32 v85, v7, 12, v6
	v_lshrrev_b32_e32 v6, 2, v86
	v_and_b32_e32 v88, 16, v6
	v_lshlrev_b32_e32 v6, 2, v86
	v_and_b32_e32 v6, 16, v6
	v_lshrrev_b32_e32 v7, 1, v86
	v_add_u32_e32 v90, 6, v77
	v_and_or_b32 v89, v7, 12, v6
	v_lshrrev_b32_e32 v6, 2, v90
	v_and_b32_e32 v92, 16, v6
	v_lshlrev_b32_e32 v6, 2, v90
	v_and_b32_e32 v6, 16, v6
	v_lshrrev_b32_e32 v7, 1, v90
	v_add_u32_e32 v97, 10, v77
	v_and_or_b32 v93, v7, 12, v6
	v_lshrrev_b32_e32 v7, 2, v97
	s_add_u32 s36, s12, 0x900000
	v_and_b32_e32 v99, 16, v7
	v_lshlrev_b32_e32 v7, 2, v97
	s_addc_u32 s37, s13, 0
	s_load_dwordx2 s[12:13], s[0:1], 0x8
	s_load_dwordx4 s[4:7], s[0:1], 0x20
	s_load_dwordx4 s[8:11], s[0:1], 0x58
	s_load_dwordx2 s[14:15], s[0:1], 0x30
	s_load_dwordx2 s[16:17], s[0:1], 0x78
	v_and_b32_e32 v7, 16, v7
	v_lshrrev_b32_e32 v8, 1, v97
	v_add_u32_e32 v101, 12, v77
	v_and_or_b32 v100, v8, 12, v7
	v_lshrrev_b32_e32 v7, 2, v101
	v_and_b32_e32 v103, 16, v7
	v_lshlrev_b32_e32 v7, 2, v101
	v_and_b32_e32 v7, 16, v7
	v_lshrrev_b32_e32 v8, 1, v101
	v_add_u32_e32 v105, 14, v77
	s_lshl_b32 s18, s73, 5
	v_add_u32_e32 v94, 8, v77
	v_and_or_b32 v104, v8, 12, v7
	v_lshrrev_b32_e32 v7, 2, v105
	v_and_b32_e32 v4, 31, v2
	v_lshl_add_u32 v66, v3, 4, s18
	v_lshrrev_b32_e32 v5, 2, v77
	v_lshlrev_b32_e32 v3, 2, v3
	v_lshrrev_b32_e32 v6, 2, v94
	v_and_b32_e32 v107, 16, v7
	v_lshlrev_b32_e32 v7, 2, v105
	v_lshlrev_b32_e32 v2, 2, v4
	v_mov_b32_e32 v69, 0
	v_mul_u32_u24_e32 v76, 0x840, v4
	v_lshlrev_b32_e32 v78, 4, v4
	v_lshlrev_b32_e32 v4, 3, v4
	s_movk_i32 s18, 0x210
	v_and_b32_e32 v80, 0x7f, v77
	v_and_b32_e32 v81, 16, v5
	v_and_b32_e32 v3, 16, v3
	v_lshrrev_b32_e32 v5, 1, v77
	v_and_b32_e32 v83, 0x7f, v82
	v_and_b32_e32 v87, 0x7f, v86
	v_and_b32_e32 v91, 0x7f, v90
	v_and_b32_e32 v95, 0x7f, v94
	v_and_b32_e32 v96, 16, v6
	v_lshrrev_b32_e32 v6, 1, v94
	v_and_b32_e32 v98, 0x7f, v97
	v_and_b32_e32 v102, 0x7f, v101
	v_and_b32_e32 v106, 0x7f, v105
	v_and_b32_e32 v7, 16, v7
	v_lshrrev_b32_e32 v8, 1, v105
	v_ashrrev_i32_e32 v67, 31, v66
	v_lshlrev_b32_e32 v75, 1, v66
	v_mul_lo_u32 v79, v77, s18
	v_and_or_b32 v108, v8, 12, v7
	v_or_b32_e32 v109, 0x80, v80
	v_or_b32_e32 v110, 0x80, v83
	v_or_b32_e32 v111, 0x80, v87
	v_or_b32_e32 v112, 0x80, v91
	v_or_b32_e32 v113, 0x80, v95
	v_or_b32_e32 v114, 0x80, v98
	v_or_b32_e32 v115, 0x80, v102
	v_or_b32_e32 v116, 0x80, v106
	v_and_or_b32 v117, v5, 12, v3
	v_and_or_b32 v118, v6, 12, v3
	s_mov_b32 s19, 0
	s_sub_i32 s38, 0, s72
	s_sub_i32 s39, 0x137f, s72
	v_lshlrev_b32_e32 v70, 2, v2
	v_mov_b32_e32 v71, v69
	s_movk_i32 s40, 0xff00
	s_movk_i32 s41, 0xf7ff
	s_movk_i32 s42, 0xffe3
	v_lshlrev_b32_e32 v68, 1, v4
	s_mov_b32 s43, 0
	s_mov_b32 s44, s72
	s_cmp_lg_u32 s98, 0
	s_cbranch_scc1 .Ldc_ovr
	v_readlane_b32 s100, v254, 2
	s_movk_i32 s101, 0x137f
	s_nop 1
	s_mov_b32 s99, s100
	s_cmpk_lg_i32 s100, 0x100
	s_cbranch_scc1 .LBB0_33
	s_cmpk_lt_i32 s72, 0x80
	s_cbranch_scc1 .Ldc_lowhalf
	s_addk_i32 s44, 3040
	s_sub_i32 s38, 0, s44
	s_sub_i32 s39, 0x137f, s44
	s_branch .LBB0_33
.Ldc_lowhalf:
	s_addk_i32 s44, 2496
	s_sub_i32 s38, 0, s44
	s_sub_i32 s39, 0x137f, s44
	s_movk_i32 s100, 800
	s_branch .LBB0_33

; __global__ void __launch_bounds__(NTHREADS, 2) mega_fwd(Args args) {
;     ...
;         for (int it = bid; it < DEPTH * I_LAYER; it += G, nbuf ^= 1) {
;             const int itr = DEPTH * I_LAYER - 1 - it;
.Ldc_setup:
	v_readlane_b32 s4, v255, 28
	v_readlane_b32 s0, v255, 62
	v_readlane_b32 s1, v255, 63
	v_readlane_b32 s12, v254, 0
	v_readlane_b32 s13, v254, 1
	v_mov_b32_e32 v2, v211
	s_cmp_lg_u32 s4, 0
	s_cselect_b32 s4, 2, 0
	s_and_b32 s5, s98, 3
	s_add_i32 s4, s4, s5
	s_lshr_b32 s5, s98, 2
	s_lshl_b32 s4, s4, 2
	s_or_b32 s4, s4, s5
	s_mov_b32 s99, 1
	s_mov_b32 s101, 0
	s_cmp_eq_u32 s4, 4
	s_cselect_b32 s99, 2144, s99
	s_cselect_b32 s101, 2495, s101
	s_cmp_eq_u32 s4, 5
	s_cselect_b32 s99, 2624, s99
	s_cselect_b32 s101, 3167, s101
	s_cmp_eq_u32 s4, 8
	s_cselect_b32 s99, 0, s99
	s_cselect_b32 s101, 127, s101
	s_cmp_eq_u32 s4, 9
	s_cselect_b32 s99, 1376, s99
	s_cselect_b32 s101, 2143, s101
	s_cmp_eq_u32 s4, 12
	s_cselect_b32 s99, 128, s99
	s_cselect_b32 s101, 383, s101
	s_cmp_eq_u32 s4, 13
	s_cselect_b32 s99, 736, s99
	s_cselect_b32 s101, 1375, s101
	s_cmp_eq_u32 s4, 16
	s_cselect_b32 s99, 384, s99
	s_cselect_b32 s101, 735, s101
	s_cmp_gt_i32 s99, s101
	s_cbranch_scc1 .Ldc_finish
	s_sub_i32 s5, s72, 0x80
	s_add_i32 s99, s99, s5
	s_cmp_gt_i32 s99, s101
	s_cbranch_scc1 .Ldc_nextpass
	s_movk_i32 s100, 0x80
	s_waitcnt lgkmcnt(0)
	s_nop 4
	s_branch .Ldc_pre

; __global__ void __launch_bounds__(NTHREADS, 2) mega_fwd(Args args) {
;     ...
;         for (int it = bid; it < DEPTH * I_LAYER; it += G, nbuf ^= 1) {
;             const int itr = DEPTH * I_LAYER - 1 - it;
;             const int l = itr / I_LAYER; int r = itr - l * I_LAYER;
;             unsigned char* WL = P_WL(l);
;             const float* W; int K, N, mode = 0; bf16* WT; const float* rg = nullptr;
;             if (r < 3 * I_GU) { const int w = r / I_GU; r -= w * I_GU;
;                 if (w < 2) { W = args.in[2 + w] + (size_t)l * D * FF; K = D; N = FF; WT = (bf16*)(WL + OFF_WGU1); rg = args.in[1] + (size_t)l * D; mode = 1 + w; }
;                 else { W = args.in[4] + (size_t)l * FF * D; K = FF; N = D; WT = (bf16*)(WL + OFF_WD1); } }
;             else if ((r -= 3 * I_GU) < 3 * I_GU) { const int w = r / I_GU; r -= w * I_GU;
;                 if (w < 2) { W = args.in[13 + w] + (size_t)l * D * FF; K = D; N = FF; WT = (bf16*)(WL + OFF_WGU2); rg = args.in[12] + (size_t)l * D; mode = 1 + w; }
;                 else { W = args.in[15] + (size_t)l * FF * D; K = FF; N = D; WT = (bf16*)(WL + OFF_WD2); } }
;             else if ((r -= 3 * I_GU) < I_IN) { W = args.in[6] + (size_t)l * D * INW; K = D; N = INW; WT = (bf16*)(WL + OFF_WIN); rg = args.in[5] + (size_t)l * D; mode = 3; }
;             else { r -= I_IN; W = args.in[11] + (size_t)l * D * D; K = D; N = D; WT = (bf16*)(WL + OFF_WOUT); }
;             tr_item_cu(W, K, N, WT, rg, mode, lds + nbuf * TC_BUF, r, wave, lane);
;         }
.Ldc_nextpass:
	s_add_i32 s98, s98, 4
	s_branch .Ldc_setup
.Ldc_finish:
	s_waitcnt vmcnt(0) lgkmcnt(0)
	ds_read_b32 v96, v1 offset:0
	ds_read_b32 v97, v1 offset:256
	ds_read_b32 v130, v1 offset:512
	ds_read_b32 v131, v1 offset:768
	ds_read_b32 v132, v1 offset:1024
	ds_read_b32 v133, v1 offset:1280
	ds_read_b32 v134, v1 offset:1536
	ds_read_b32 v135, v1 offset:1792
	s_waitcnt lgkmcnt(0)
	v_readlane_b32 s2, v0, 2
	v_readlane_b32 s3, v0, 3
	v_readlane_b32 s4, v0, 4
	v_readlane_b32 s5, v0, 5
	v_readlane_b32 s6, v0, 6
	v_readlane_b32 s7, v0, 7
	v_readlane_b32 s8, v0, 8
	v_readlane_b32 s9, v0, 9
	v_readlane_b32 s10, v0, 10
	v_readlane_b32 s11, v0, 11
	v_readlane_b32 s12, v0, 12
	v_readlane_b32 s13, v0, 13
	v_readlane_b32 s14, v0, 14
	v_readlane_b32 s15, v0, 15
	v_readlane_b32 s16, v0, 16
	v_readlane_b32 s17, v0, 17
	v_readlane_b32 s18, v0, 18
	v_readlane_b32 s19, v0, 19
	v_readlane_b32 s20, v0, 20
	v_readlane_b32 s21, v0, 21
	v_readlane_b32 s22, v0, 22
	v_readlane_b32 s23, v0, 23
	v_readlane_b32 s24, v0, 24
	v_readlane_b32 s25, v0, 25
	v_readlane_b32 s26, v0, 26
	v_readlane_b32 s27, v0, 27
	v_readlane_b32 s28, v0, 28
	v_readlane_b32 s29, v0, 29
	v_readlane_b32 s30, v0, 30
	v_readlane_b32 s31, v0, 31
	v_readlane_b32 s32, v0, 32
	v_readlane_b32 s33, v0, 33
	v_readlane_b32 s34, v0, 34
	v_readlane_b32 s35, v0, 35
	v_readlane_b32 s36, v0, 36
	v_readlane_b32 s37, v0, 37
	v_readlane_b32 s38, v0, 38
	v_readlane_b32 s39, v0, 39
	v_readlane_b32 s40, v0, 40
	v_readlane_b32 s41, v0, 41
	v_readlane_b32 s42, v0, 42
	v_readlane_b32 s43, v0, 43
	v_readlane_b32 s44, v0, 44
	v_readlane_b32 s45, v0, 45
	v_readlane_b32 s46, v0, 46
	v_readlane_b32 s47, v0, 47
	v_readlane_b32 s48, v0, 48
	s_nop 4
	s_and_b32 s98, s98, 3
	s_cmp_eq_u32 s98, 1
	s_mov_b32 s98, 0
	s_cbranch_scc1 .Ldc_retA
	s_branch .Ldc_retB
